# speedup vs baseline: 1.0176x; 1.0176x over previous
; __device__ void attn_a_item(const Params& p, int layer, int b, int h, int q128, unsigned char* smem) {
;     ...
;     {
;         const unsigned* km = reinterpret_cast<const unsigned*>(p.ws + WS_LAM) + SM_KMAX + layer * 16 + (b * 4 + h) * 2;
; #pragma unroll
;         for (int mp = 0; mp < 2; ++mp) {
;             const float kmaxn = sqrtf(__uint_as_float(km[mp]));
; #pragma unroll
;             for (int qt = 0; qt < 2; ++qt) {
;                 float qn = 0.f;
; #pragma unroll
;                 for (int j = 0; j < 8; ++j) { float v = __uint_as_float(((unsigned)(unsigned short)qf[mp][qt][j]) << 16); qn += v * v; }
;                 qn += __shfl_xor(qn, 16); qn += __shfl_xor(qn, 32);
;                 ub[mp][qt] = c2 * sqrtf(qn) * kmaxn * 1.02f + 0.01f;
;                 ubm = fmaxf(ubm, ub[mp][qt]);
;                 ls[mp][qt] = f32x4{0.f, 0.f, 0.f, 0.f};
; #pragma unroll
;                 for (int et = 0; et < 4; ++et) o[mp][qt][et] = f32x4{0.f, 0.f, 0.f, 0.f};
;             }
;         }
;     }
;     const float thr = 150.5f;
;     f32x4 cb[2];
;     {
;         const float sc = slope2 / c2;
; #pragma unroll
;         for (int t = 0; t < 2; ++t)
; #pragma unroll
;             for (int r = 0; r < 4; ++r) cb[t][r] = sc * (float)(t * 4 + r);
;     }
;     const int gmax = q128 * 4 + qg;
;     const int jtop = q128 * 2 + 1;
;     const int jlow = max(0, (int)floorf(((float)(q128 * 128) - thr / slope2) * (1.f / 64.f)) - 1);
;     const int nsteps = (jtop - jlow + 4) / 4;
;     TileRegs tr0, tr1;
;     auto tl = [&](int j) { return (j > 0 ? j : 0) * 64; };
.LBB0_434:
	s_max_i32 s62, s65, 1
	s_sub_i32 s62, s64, s62
	v_bfe_u32 v174, v172, 4, 2
	s_add_i32 s62, s62, 6
	v_lshlrev_b32_e32 v156, 3, v174
	s_cmp_lt_i32 s62, 4
	v_ashrrev_i32_e32 v178, 8, v172
	s_cbranch_scc1 .LBB0_449
	v_cndmask_b32_e64 v20, v28, v29, s[4:5]
	v_cndmask_b32_e64 v20, v20, v30, s[6:7]
	v_mul_f32_e32 v21, 0x37800000, v20
	v_cndmask_b32_e64 v20, v20, v21, s[2:3]
	v_cndmask_b32_e64 v21, v33, v34, s[10:11]
	v_cndmask_b32_e64 v21, v21, v35, s[12:13]
	v_mul_f32_e32 v22, 0x37800000, v21
	v_cndmask_b32_e64 v21, v21, v22, s[8:9]
	v_cndmask_b32_e64 v22, v38, v39, s[18:19]
	v_cndmask_b32_e64 v22, v22, v41, s[20:21]
	v_mul_f32_e32 v23, 0x37800000, v22
	v_cndmask_b32_e64 v22, v22, v23, s[14:15]
	v_cndmask_b32_e64 v23, v42, v43, s[22:23]
	v_cmp_class_f32_e32 vcc, v27, v213
	v_cndmask_b32_e64 v23, v23, v44, s[24:25]
	v_lshl_add_u64 v[158:159], v[2:3], 1, s[92:93]
	v_cndmask_b32_e32 v20, v20, v27, vcc
	v_cmp_class_f32_e32 vcc, v32, v213
	v_mul_f32_e32 v27, 0x37800000, v23
	v_cndmask_b32_e64 v23, v23, v27, s[16:17]
	v_cndmask_b32_e32 v21, v21, v32, vcc
	v_cndmask_b32_e64 v27, v46, v47, s[28:29]
	v_cmp_class_f32_e32 vcc, v37, v213
	v_cndmask_b32_e64 v27, v27, v48, s[30:31]
	v_lshl_or_b32 v3, v157, 6, v0
	v_mul_f32_e32 v0, 0x3e8293ee, v21
	v_cndmask_b32_e32 v22, v22, v37, vcc
	v_cmp_class_f32_e32 vcc, v40, v213
	v_mul_f32_e32 v28, 0x37800000, v27
	v_mul_f32_e32 v0, v20, v0
	v_cndmask_b32_e32 v23, v23, v40, vcc
	v_cndmask_b32_e64 v27, v27, v28, s[26:27]
	v_cmp_class_f32_e32 vcc, v45, v213
	v_fmamk_f32 v179, v0, 0x3f828f5c, v206
	v_mul_f32_e32 v0, 0x3e8293ee, v22
	v_cndmask_b32_e32 v27, v27, v45, vcc
	v_mul_f32_e32 v0, v20, v0
	v_cndmask_b32_e64 v28, v50, v51, s[36:37]
	v_fmamk_f32 v180, v0, 0x3f828f5c, v206
	v_mul_f32_e32 v0, 0x3e8293ee, v27
	v_cndmask_b32_e64 v28, v28, v52, s[38:39]
	v_mul_f32_e32 v0, v23, v0
	s_mov_b32 s4, 0x3e8293ee
	v_mul_f32_e32 v29, 0x37800000, v28
	v_fmamk_f32 v181, v0, 0x3f828f5c, v206
	v_div_scale_f32 v0, s[2:3], s4, s4, v176
	v_cndmask_b32_e64 v28, v28, v29, s[34:35]
	v_cmp_class_f32_e32 vcc, v49, v213
	v_rcp_f32_e32 v20, v0
	s_mov_b32 s2, 2.0
	v_cndmask_b32_e32 v28, v28, v49, vcc
	v_mul_f32_e32 v21, 0x3e8293ee, v28
	v_mul_f32_e32 v21, v23, v21
	v_fmamk_f32 v182, v21, 0x3f828f5c, v206
	v_fma_f32 v21, -v0, v20, 1.0
	v_fmac_f32_e32 v20, v21, v20
	v_div_scale_f32 v21, vcc, v176, s4, v176
	v_mul_f32_e32 v22, v21, v20
	v_fma_f32 v23, -v0, v22, v21
	v_fmac_f32_e32 v22, v23, v20
	v_fma_f32 v0, -v0, v22, v21
	v_div_fmas_f32 v0, v0, v20, v22
	v_div_fixup_f32 v0, v0, s4, v176
	s_mov_b32 s3, 0x40400000
	v_pk_mul_f32 v[102:103], v[0:1], s[2:3] op_sel_hi:[0,1]
	s_mov_b32 s2, 0x40c00000
	s_mov_b32 s3, 0x40e00000
	v_pk_mul_f32 v[106:107], v[0:1], s[2:3] op_sel_hi:[0,1]
	s_mov_b32 s2, 4.0
	v_lshlrev_b32_e32 v2, 2, v157
	s_mov_b32 s3, 0x40a00000
	v_and_b32_e32 v2, 32, v2
	v_mul_f32_e32 v100, 0, v0
	v_mov_b32_e32 v101, v0
	v_pk_mul_f32 v[104:105], v[0:1], s[2:3] op_sel_hi:[0,1]
	s_ashr_i32 s2, s62, 31
	v_lshlrev_b32_e32 v0, 15, v178
	s_lshr_b32 s2, s2, 30
	v_bitop3_b32 v187, v0, v2, v3 bitop3:0xf6
	v_mov_b32_e32 v2, v1
	v_mov_b32_e32 v3, v1
	v_lshl_add_u64 v[160:161], v[24:25], 1, s[46:47]
	s_add_i32 s62, s62, s2
	v_sub_u32_e32 v185, v26, v156
	v_mov_b32_e32 v0, v1
	v_mov_b64_e32 v[78:79], v[2:3]
	v_mov_b64_e32 v[54:55], v[2:3]
	v_mov_b64_e32 v[62:63], v[2:3]
	v_mov_b64_e32 v[70:71], v[2:3]
	v_mov_b64_e32 v[50:51], v[2:3]
	v_mov_b64_e32 v[26:27], v[2:3]
	v_mov_b64_e32 v[34:35], v[2:3]
	v_mov_b64_e32 v[42:43], v[2:3]
	v_mov_b64_e32 v[82:83], v[2:3]
	v_mov_b64_e32 v[58:59], v[2:3]
	v_mov_b64_e32 v[66:67], v[2:3]
	v_mov_b64_e32 v[74:75], v[2:3]
	v_mov_b64_e32 v[86:87], v[2:3]
	v_mov_b64_e32 v[90:91], v[2:3]
	v_mov_b64_e32 v[94:95], v[2:3]
	v_mov_b64_e32 v[98:99], v[2:3]
	v_mov_b64_e32 v[38:39], v[2:3]
	v_mov_b64_e32 v[30:31], v[2:3]
	v_mov_b64_e32 v[22:23], v[2:3]
	v_mov_b64_e32 v[46:47], v[2:3]
	v_lshl_or_b32 v183, s45, 2, v173
	s_ashr_i32 s24, s62, 2
	v_subrev_u32_e32 v184, 31, v171
	v_lshlrev_b32_e32 v186, 1, v178
	s_mov_b64 s[16:17], 0
	s_mov_b32 s25, 0
	v_mov_b64_e32 v[76:77], v[0:1]
	v_mov_b64_e32 v[52:53], v[0:1]
	v_mov_b64_e32 v[60:61], v[0:1]
	v_mov_b64_e32 v[68:69], v[0:1]
	v_mov_b64_e32 v[48:49], v[0:1]
	v_mov_b64_e32 v[24:25], v[0:1]
	v_mov_b64_e32 v[32:33], v[0:1]
	v_mov_b64_e32 v[40:41], v[0:1]
	v_mov_b64_e32 v[80:81], v[0:1]
	v_mov_b64_e32 v[56:57], v[0:1]
	v_mov_b64_e32 v[64:65], v[0:1]
	v_mov_b64_e32 v[72:73], v[0:1]
	v_mov_b64_e32 v[84:85], v[0:1]
	v_mov_b64_e32 v[88:89], v[0:1]
	v_mov_b64_e32 v[92:93], v[0:1]
	v_mov_b64_e32 v[96:97], v[0:1]
	v_mov_b64_e32 v[36:37], v[0:1]
	v_mov_b64_e32 v[28:29], v[0:1]
	v_mov_b64_e32 v[20:21], v[0:1]
	v_mov_b64_e32 v[44:45], v[0:1]
	s_mov_b32 s26, 0
	s_movk_i32 s64, 0x3c0
	s_mov_b32 s65, 0x16400000
	v_mov_b32_e32 v220, s44
	v_mov_b32_e32 v221, s44
	v_mov_b32_e32 v222, s44
	v_mov_b32_e32 v223, s44
	s_branch .LBB0_437

; template <bool MASKED>
; __device__ __forceinline__ void diff_group(const unsigned char* st, int kgp, int fo, const bf16x8 (&qf)[2][2], f32x4 (&o)[2][2][4], f32x4 (&ls)[2][2],
;                                            const f32x4 (&cb)[2], float c2, float slope2, const float (&ub)[2][2], int d0) {
;     bf16x8 kf[2][2], vf[4];
; #pragma unroll
;     for (int t = 0; t < 2; ++t)
; #pragma unroll
;         for (int c = 0; c < 2; ++c) kf[t][c] = lds_frag(st + ((kgp * 2 + t) * 2 + c) * 1024 + fo);
; #pragma unroll
;     for (int et = 0; et < 4; ++et) vf[et] = lds_frag(st + 8192 + (et * 2 + kgp) * 1024 + fo);
;     const short one = (short)0x3F80;
;     const bf16x8 ones = {one, one, one, one, one, one, one, one};
; #pragma unroll
;     for (int qt = 0; qt < 2; ++qt) {
;         const int dq = d0 + qt * 16;
;         const float offq = -slope2 * (float)dq;
; #pragma unroll
;         for (int mp = 0; mp < 2; ++mp) {
;             f32x4 s[2];
; #pragma unroll
;             for (int t = 0; t < 2; ++t) s[t] = mfma16(kf[t][mp], qf[mp][qt], cb[t]);
;             if (MASKED) {
; #pragma unroll
;                 for (int j = 0; j < 8; ++j) if (dq - j < 0) s[j >> 2][j & 3] = -INFINITY;
;             }
;             const float off = offq - ub[mp][qt];
;             float pj[8];
; #pragma unroll
;             for (int j = 0; j < 8; ++j) pj[j] = ex2(fmaf(s[j >> 2][j & 3], c2, off));
;             u32x4 pu = {pk2(pj[0], pj[1]), pk2(pj[2], pj[3]), pk2(pj[4], pj[5]), pk2(pj[6], pj[7])};
;             bf16x8 pf = __builtin_bit_cast(bf16x8, pu);
; #pragma unroll
;             for (int et = 0; et < 4; ++et) o[mp][qt][et] = mfma16(vf[et], pf, o[mp][qt][et]);
;             ls[mp][qt] = mfma16(ones, pf, ls[mp][qt]);
;         }
;     }
; }
; __device__ void attn_a_item(const Params& p, int layer, int b, int h, int q128, unsigned char* smem) {
;     ...
;     for (int t = 0; t < nsteps; ++t) {
;         const int jn = jtop - 4 * (t + 1);
;         unsigned char* nst = smem + (sidx ^ 1) * 65536;
;         attn_tile_load(tr0, kbase, vbase, tl(jn), tofs);
;         attn_tile_load(tr1, kbase, vbase, tl(jn - 2), tofs);
;         const unsigned char* st0 = smem + sidx * 65536 + strm * 32768;
;         const int jw = jtop - 4 * t - 2 * strm;
; #pragma unroll 1
;         for (int gi = 0; gi < 4; ++gi) {
;             if (gi == 2) {
;                 attn_tile_store(tr0, nst, tofs);
.LBB0_437:
	s_mov_b32 s4, s26
	s_add_i32 s26, s26, 1
	s_lshl_b32 s2, s26, 2
	s_sub_i32 s5, s82, s2
	s_max_i32 s6, s5, 0
	s_lshl_b32 s2, s6, 6
	v_mad_u64_u32 v[2:3], s[2:3], s2, v209, v[158:159]
	s_max_i32 s2, s5, 2
	s_lshl_b32 s62, s6, 7
	s_lshl_b32 s2, s2, 6
	v_lshl_add_u64 v[108:109], v[160:161], 0, s[62:63]
	s_add_i32 s62, s2, 0xffffff80
	global_load_dwordx4 v[112:115], v[2:3], off offset:512
	s_nop 0
	global_load_dwordx4 v[108:111], v[108:109], off
	v_mad_u64_u32 v[2:3], s[2:3], s62, v209, v[158:159]
	v_lshl_add_u64 v[120:121], s[62:63], 1, v[160:161]
	global_load_dwordx4 v[116:119], v[2:3], off offset:512
	s_nop 0
	global_load_dwordx4 v[120:123], v[120:121], off
	s_max_i32 s2, s5, 1
	s_lshl_b32 s2, s2, 6
	s_sub_i32 s62, s2, 64
	v_mad_u64_u32 v[2:3], s[2:3], s62, v209, v[158:159]
	s_max_i32 s2, s5, 3
	s_lshl_b32 s2, s2, 6
	s_mov_b32 s6, s25
	s_xor_b32 s25, s25, 1
	v_lshl_add_u64 v[162:163], s[62:63], 1, v[160:161]
	s_add_i32 s62, s2, 0xffffff40
	s_lshl_b32 s27, s25, 16
	v_mad_u64_u32 v[164:165], s[2:3], s62, v209, v[158:159]
	v_lshl_add_u64 v[166:167], s[62:63], 1, v[160:161]
	v_lshl_add_u32 v0, s4, 2, v186
	v_lshl_add_u32 v190, s6, 16, v187
	s_mov_b32 s28, 0
	v_readfirstlane_b32 s8, v186
	v_readfirstlane_b32 s9, v183
	v_readfirstlane_b32 s10, v184
	s_lshl_b32 s11, s4, 2
	s_add_i32 s11, s11, s8
	s_sub_i32 s11, s82, s11
	s_lshl_b32 s11, s11, 1
	s_add_i32 s12, s11, 1
	s_add_i32 s13, s11, -2
	s_cmp_lt_i32 s13, 0
	s_cbranch_scc1 .LBB0_441
	s_cmp_ge_i32 s12, s9
	s_cbranch_scc1 .LBB0_441
	s_cmp_lg_u64 s[16:17], 0
	s_cbranch_scc1 .LBB0_441
	s_lshl_b32 s14, s13, 5
	s_sub_i32 s14, s10, s14
	v_cvt_f32_i32_e32 v124, s14
	s_mov_b32 s2, 0x43168000
	v_mul_f32_e32 v124, v176, v124
	v_cmp_nlt_f32_e32 vcc, s2, v124
	s_and_b64 vcc, exec, vcc
	s_cbranch_vccz .LBB0_441
	s_lshl_b32 s14, s12, 5
	v_subrev_u32_e32 v193, s14, v185
	ds_read_b128 v[152:155], v190 offset:4096
	ds_read_b128 v[144:147], v190 offset:5120
	ds_read_b128 v[148:151], v190 offset:6144
	ds_read_b128 v[140:143], v190 offset:7168
	ds_read_b128 v[124:127], v190 offset:9216
	ds_read_b128 v[128:131], v190 offset:11264
	ds_read_b128 v[132:135], v190 offset:13312
	ds_read_b128 v[136:139], v190 offset:15360
	v_cvt_f32_i32_e32 v204, v193
	v_add_u32_e32 v193, 16, v193
	v_cvt_f32_i32_e32 v205, v193
	v_mul_f32_e64 v192, -v176, v204
	v_sub_f32_e32 v194, v192, v179
	v_sub_f32_e32 v192, v192, v181
	s_waitcnt lgkmcnt(4)
	v_mfma_f32_16x16x32_bf16 v[196:199], v[152:155], v[4:7], v[100:103]
	v_mfma_f32_16x16x32_bf16 v[200:203], v[148:151], v[4:7], v[104:107]
	v_mfma_f32_16x16x32_bf16 v[216:219], v[144:147], v[12:15], v[100:103]
	v_mfma_f32_16x16x32_bf16 v[224:227], v[140:143], v[12:15], v[104:107]
	v_mfma_f32_16x16x32_bf16 v[152:155], v[152:155], v[8:11], v[100:103]
	v_mfma_f32_16x16x32_bf16 v[148:151], v[148:151], v[8:11], v[104:107]
	v_fma_f32 v193, -v176, v205, -v180
	v_fma_f32 v195, -v176, v205, -v182
	v_mfma_f32_16x16x32_bf16 v[144:147], v[144:147], v[16:19], v[100:103]
	v_fmamk_f32 v196, v196, 0x3e8293ee, v194
	v_fmamk_f32 v197, v197, 0x3e8293ee, v194
	v_fmamk_f32 v198, v198, 0x3e8293ee, v194
	v_fmamk_f32 v199, v199, 0x3e8293ee, v194
	v_mfma_f32_16x16x32_bf16 v[140:143], v[140:143], v[16:19], v[104:107]
	ds_read_b128 v[236:239], v190 offset:0
	ds_read_b128 v[240:243], v190 offset:1024
	ds_read_b128 v[244:247], v190 offset:2048
	ds_read_b128 v[248:251], v190 offset:3072
	v_fmamk_f32 v200, v200, 0x3e8293ee, v194
	v_fmamk_f32 v201, v201, 0x3e8293ee, v194
	v_fmamk_f32 v202, v202, 0x3e8293ee, v194
	v_fmamk_f32 v203, v203, 0x3e8293ee, v194
	v_exp_f32_e32 v196, v196
	v_exp_f32_e32 v197, v197
	v_exp_f32_e32 v198, v198
	v_exp_f32_e32 v199, v199
	v_exp_f32_e32 v200, v200
	v_exp_f32_e32 v201, v201
	v_exp_f32_e32 v202, v202
	v_exp_f32_e32 v203, v203
	v_cvt_pk_bf16_f32 v228, v196, v197
	v_cvt_pk_bf16_f32 v229, v198, v199
	v_cvt_pk_bf16_f32 v230, v200, v201
	v_cvt_pk_bf16_f32 v231, v202, v203
	v_fmamk_f32 v216, v216, 0x3e8293ee, v192
	v_fmamk_f32 v217, v217, 0x3e8293ee, v192
	s_waitcnt lgkmcnt(4)
	v_mfma_f32_16x16x32_bf16 v[72:75], v[124:127], v[228:231], v[72:75]
	v_fmamk_f32 v218, v218, 0x3e8293ee, v192
	v_fmamk_f32 v219, v219, 0x3e8293ee, v192
	v_fmamk_f32 v224, v224, 0x3e8293ee, v192
	v_fmamk_f32 v225, v225, 0x3e8293ee, v192
	v_mfma_f32_16x16x32_bf16 v[64:67], v[128:131], v[228:231], v[64:67]
	v_fmamk_f32 v226, v226, 0x3e8293ee, v192
	v_fmamk_f32 v227, v227, 0x3e8293ee, v192
	v_exp_f32_e32 v216, v216
	v_exp_f32_e32 v217, v217
	v_mfma_f32_16x16x32_bf16 v[56:59], v[132:135], v[228:231], v[56:59]
	v_exp_f32_e32 v218, v218
	v_exp_f32_e32 v219, v219
	v_exp_f32_e32 v224, v224
	v_mfma_f32_16x16x32_bf16 v[80:83], v[136:139], v[228:231], v[80:83]
	v_exp_f32_e32 v225, v225
	v_exp_f32_e32 v226, v226
	v_exp_f32_e32 v227, v227
	v_mfma_f32_16x16x32_bf16 v[96:99], v[220:223], v[228:231], v[96:99]
	v_cvt_pk_bf16_f32 v232, v216, v217
	v_cvt_pk_bf16_f32 v233, v218, v219
	v_cvt_pk_bf16_f32 v234, v224, v225
	v_cvt_pk_bf16_f32 v235, v226, v227
	v_fmamk_f32 v152, v152, 0x3e8293ee, v193
	v_fmamk_f32 v153, v153, 0x3e8293ee, v193
	v_mfma_f32_16x16x32_bf16 v[68:71], v[124:127], v[232:235], v[68:71]
	v_fmamk_f32 v154, v154, 0x3e8293ee, v193
	v_fmamk_f32 v155, v155, 0x3e8293ee, v193
	v_fmamk_f32 v148, v148, 0x3e8293ee, v193
	v_fmamk_f32 v149, v149, 0x3e8293ee, v193
	v_mfma_f32_16x16x32_bf16 v[60:63], v[128:131], v[232:235], v[60:63]
	v_fmamk_f32 v150, v150, 0x3e8293ee, v193
	v_fmamk_f32 v151, v151, 0x3e8293ee, v193
	v_exp_f32_e32 v152, v152
	v_exp_f32_e32 v153, v153
	v_mfma_f32_16x16x32_bf16 v[52:55], v[132:135], v[232:235], v[52:55]
	v_exp_f32_e32 v154, v154
	v_exp_f32_e32 v155, v155
	v_exp_f32_e32 v148, v148
; __device__ __forceinline__ f32x4 mfma16(bf16x8 a, bf16x8 b, f32x4 c) { return __builtin_amdgcn_mfma_f32_16x16x32_bf16(a, b, c, 0, 0, 0); }
; __device__ __forceinline__ float ex2(float x) { return __builtin_amdgcn_exp2f(x); }
; template <bool MASKED>
; __device__ __forceinline__ void diff_group(const unsigned char* st, int kgp, int fo, const bf16x8 (&qf)[2][2], f32x4 (&o)[2][2][4], f32x4 (&ls)[2][2],
;                                            const f32x4 (&cb)[2], float c2, float slope2, const float (&ub)[2][2], int d0) {
;     bf16x8 kf[2][2], vf[4];
; #pragma unroll
;     for (int t = 0; t < 2; ++t)
; #pragma unroll
;         for (int c = 0; c < 2; ++c) kf[t][c] = lds_frag(st + ((kgp * 2 + t) * 2 + c) * 1024 + fo);
; #pragma unroll
;     for (int et = 0; et < 4; ++et) vf[et] = lds_frag(st + 8192 + (et * 2 + kgp) * 1024 + fo);
;     const short one = (short)0x3F80;
;     const bf16x8 ones = {one, one, one, one, one, one, one, one};
; #pragma unroll
;     for (int qt = 0; qt < 2; ++qt) {
;         const int dq = d0 + qt * 16;
;         const float offq = -slope2 * (float)dq;
; #pragma unroll
;         for (int mp = 0; mp < 2; ++mp) {
;             f32x4 s[2];
; #pragma unroll
;             for (int t = 0; t < 2; ++t) s[t] = mfma16(kf[t][mp], qf[mp][qt], cb[t]);
;             if (MASKED) {
; #pragma unroll
;                 for (int j = 0; j < 8; ++j) if (dq - j < 0) s[j >> 2][j & 3] = -INFINITY;
;             }
;             const float off = offq - ub[mp][qt];
;             float pj[8];
; #pragma unroll
;             for (int j = 0; j < 8; ++j) pj[j] = ex2(fmaf(s[j >> 2][j & 3], c2, off));
;             u32x4 pu = {pk2(pj[0], pj[1]), pk2(pj[2], pj[3]), pk2(pj[4], pj[5]), pk2(pj[6], pj[7])};
;             bf16x8 pf = __builtin_bit_cast(bf16x8, pu);
; #pragma unroll
;             for (int et = 0; et < 4; ++et) o[mp][qt][et] = mfma16(vf[et], pf, o[mp][qt][et]);
;             ls[mp][qt] = mfma16(ones, pf, ls[mp][qt]);
;         }
;     }
; }
	v_mfma_f32_16x16x32_bf16 v[76:79], v[136:139], v[232:235], v[76:79]
	v_exp_f32_e32 v149, v149
	v_exp_f32_e32 v150, v150
	v_exp_f32_e32 v151, v151
	v_mfma_f32_16x16x32_bf16 v[88:91], v[220:223], v[232:235], v[88:91]
	v_cvt_pk_bf16_f32 v228, v152, v153
	v_cvt_pk_bf16_f32 v229, v154, v155
	v_cvt_pk_bf16_f32 v230, v148, v149
	v_cvt_pk_bf16_f32 v231, v150, v151
	v_fmamk_f32 v144, v144, 0x3e8293ee, v195
	v_fmamk_f32 v145, v145, 0x3e8293ee, v195
	v_mfma_f32_16x16x32_bf16 v[40:43], v[124:127], v[228:231], v[40:43]
	v_fmamk_f32 v146, v146, 0x3e8293ee, v195
	v_fmamk_f32 v147, v147, 0x3e8293ee, v195
	v_fmamk_f32 v140, v140, 0x3e8293ee, v195
	v_fmamk_f32 v141, v141, 0x3e8293ee, v195
	v_mfma_f32_16x16x32_bf16 v[32:35], v[128:131], v[228:231], v[32:35]
	v_fmamk_f32 v142, v142, 0x3e8293ee, v195
	v_fmamk_f32 v143, v143, 0x3e8293ee, v195
	v_exp_f32_e32 v144, v144
	v_exp_f32_e32 v145, v145
	v_mfma_f32_16x16x32_bf16 v[24:27], v[132:135], v[228:231], v[24:27]
	v_exp_f32_e32 v146, v146
	v_exp_f32_e32 v147, v147
	v_exp_f32_e32 v140, v140
	v_mfma_f32_16x16x32_bf16 v[48:51], v[136:139], v[228:231], v[48:51]
	v_exp_f32_e32 v141, v141
	v_exp_f32_e32 v142, v142
	v_exp_f32_e32 v143, v143
	v_mfma_f32_16x16x32_bf16 v[92:95], v[220:223], v[228:231], v[92:95]
	v_cvt_pk_bf16_f32 v232, v144, v145
	v_cvt_pk_bf16_f32 v233, v146, v147
	v_cvt_pk_bf16_f32 v234, v140, v141
	v_cvt_pk_bf16_f32 v235, v142, v143
	s_nop 1
	v_mfma_f32_16x16x32_bf16 v[36:39], v[124:127], v[232:235], v[36:39]
	v_mfma_f32_16x16x32_bf16 v[28:31], v[128:131], v[232:235], v[28:31]
	v_mfma_f32_16x16x32_bf16 v[20:23], v[132:135], v[232:235], v[20:23]
	v_mfma_f32_16x16x32_bf16 v[44:47], v[136:139], v[232:235], v[44:47]
	v_mfma_f32_16x16x32_bf16 v[84:87], v[220:223], v[232:235], v[84:87]
	ds_read_b128 v[124:127], v190 offset:8192
	ds_read_b128 v[128:131], v190 offset:10240
	ds_read_b128 v[132:135], v190 offset:12288
	ds_read_b128 v[136:139], v190 offset:14336
	v_add_f32_e32 v204, 0x42000000, v204
	v_add_f32_e32 v205, 0x42000000, v205
	v_mul_f32_e64 v192, -v176, v204
	v_sub_f32_e32 v194, v192, v179
	v_sub_f32_e32 v192, v192, v181
	s_waitcnt lgkmcnt(4)
	v_mfma_f32_16x16x32_bf16 v[196:199], v[236:239], v[4:7], v[100:103]
	v_mfma_f32_16x16x32_bf16 v[200:203], v[244:247], v[4:7], v[104:107]
	v_mfma_f32_16x16x32_bf16 v[216:219], v[240:243], v[12:15], v[100:103]
	v_mfma_f32_16x16x32_bf16 v[224:227], v[248:251], v[12:15], v[104:107]
	v_mfma_f32_16x16x32_bf16 v[236:239], v[236:239], v[8:11], v[100:103]
	v_mfma_f32_16x16x32_bf16 v[244:247], v[244:247], v[8:11], v[104:107]
	v_fma_f32 v193, -v176, v205, -v180
	v_fma_f32 v195, -v176, v205, -v182
	v_mfma_f32_16x16x32_bf16 v[240:243], v[240:243], v[16:19], v[100:103]
	v_fmamk_f32 v196, v196, 0x3e8293ee, v194
	v_fmamk_f32 v197, v197, 0x3e8293ee, v194
	v_fmamk_f32 v198, v198, 0x3e8293ee, v194
	v_fmamk_f32 v199, v199, 0x3e8293ee, v194
	v_mfma_f32_16x16x32_bf16 v[248:251], v[248:251], v[16:19], v[104:107]
	ds_read_b128 v[152:155], v190 offset:20480
	ds_read_b128 v[144:147], v190 offset:21504
	ds_read_b128 v[148:151], v190 offset:22528
	ds_read_b128 v[140:143], v190 offset:23552
	v_fmamk_f32 v200, v200, 0x3e8293ee, v194
	v_fmamk_f32 v201, v201, 0x3e8293ee, v194
	v_fmamk_f32 v202, v202, 0x3e8293ee, v194
	v_fmamk_f32 v203, v203, 0x3e8293ee, v194
	v_exp_f32_e32 v196, v196
	v_exp_f32_e32 v197, v197
	v_exp_f32_e32 v198, v198
	v_exp_f32_e32 v199, v199
	v_exp_f32_e32 v200, v200
	v_exp_f32_e32 v201, v201
	v_exp_f32_e32 v202, v202
	v_exp_f32_e32 v203, v203
	v_cvt_pk_bf16_f32 v228, v196, v197
	v_cvt_pk_bf16_f32 v229, v198, v199
	v_cvt_pk_bf16_f32 v230, v200, v201
	v_cvt_pk_bf16_f32 v231, v202, v203
	v_fmamk_f32 v216, v216, 0x3e8293ee, v192
	v_fmamk_f32 v217, v217, 0x3e8293ee, v192
	s_waitcnt lgkmcnt(4)
	v_mfma_f32_16x16x32_bf16 v[72:75], v[124:127], v[228:231], v[72:75]
	v_fmamk_f32 v218, v218, 0x3e8293ee, v192
	v_fmamk_f32 v219, v219, 0x3e8293ee, v192
	v_fmamk_f32 v224, v224, 0x3e8293ee, v192
	v_fmamk_f32 v225, v225, 0x3e8293ee, v192
	v_mfma_f32_16x16x32_bf16 v[64:67], v[128:131], v[228:231], v[64:67]
	v_fmamk_f32 v226, v226, 0x3e8293ee, v192
	v_fmamk_f32 v227, v227, 0x3e8293ee, v192
	v_exp_f32_e32 v216, v216
	v_exp_f32_e32 v217, v217
	v_mfma_f32_16x16x32_bf16 v[56:59], v[132:135], v[228:231], v[56:59]
	v_exp_f32_e32 v218, v218
	v_exp_f32_e32 v219, v219
	v_exp_f32_e32 v224, v224
	v_mfma_f32_16x16x32_bf16 v[80:83], v[136:139], v[228:231], v[80:83]
	v_exp_f32_e32 v225, v225
	v_exp_f32_e32 v226, v226
	v_exp_f32_e32 v227, v227
	v_mfma_f32_16x16x32_bf16 v[96:99], v[220:223], v[228:231], v[96:99]
	v_cvt_pk_bf16_f32 v232, v216, v217
	v_cvt_pk_bf16_f32 v233, v218, v219
	v_cvt_pk_bf16_f32 v234, v224, v225
	v_cvt_pk_bf16_f32 v235, v226, v227
	v_fmamk_f32 v236, v236, 0x3e8293ee, v193
	v_fmamk_f32 v237, v237, 0x3e8293ee, v193
	v_mfma_f32_16x16x32_bf16 v[68:71], v[124:127], v[232:235], v[68:71]
	v_fmamk_f32 v238, v238, 0x3e8293ee, v193
	v_fmamk_f32 v239, v239, 0x3e8293ee, v193
	v_fmamk_f32 v244, v244, 0x3e8293ee, v193
	v_fmamk_f32 v245, v245, 0x3e8293ee, v193
	v_mfma_f32_16x16x32_bf16 v[60:63], v[128:131], v[232:235], v[60:63]
	v_fmamk_f32 v246, v246, 0x3e8293ee, v193
	v_fmamk_f32 v247, v247, 0x3e8293ee, v193
	v_exp_f32_e32 v236, v236
	v_exp_f32_e32 v237, v237
	v_mfma_f32_16x16x32_bf16 v[52:55], v[132:135], v[232:235], v[52:55]
	v_exp_f32_e32 v238, v238
	v_exp_f32_e32 v239, v239
	v_exp_f32_e32 v244, v244
	v_mfma_f32_16x16x32_bf16 v[76:79], v[136:139], v[232:235], v[76:79]
	v_exp_f32_e32 v245, v245
	v_exp_f32_e32 v246, v246
	v_exp_f32_e32 v247, v247
	v_mfma_f32_16x16x32_bf16 v[88:91], v[220:223], v[232:235], v[88:91]
	v_cvt_pk_bf16_f32 v228, v236, v237
	v_cvt_pk_bf16_f32 v229, v238, v239
; __device__ __forceinline__ f32x4 mfma16(bf16x8 a, bf16x8 b, f32x4 c) { return __builtin_amdgcn_mfma_f32_16x16x32_bf16(a, b, c, 0, 0, 0); }
; __device__ __forceinline__ float ex2(float x) { return __builtin_amdgcn_exp2f(x); }
; template <bool MASKED>
; __device__ __forceinline__ void diff_group(const unsigned char* st, int kgp, int fo, const bf16x8 (&qf)[2][2], f32x4 (&o)[2][2][4], f32x4 (&ls)[2][2],
;                                            const f32x4 (&cb)[2], float c2, float slope2, const float (&ub)[2][2], int d0) {
;     bf16x8 kf[2][2], vf[4];
; #pragma unroll
;     for (int t = 0; t < 2; ++t)
; #pragma unroll
;         for (int c = 0; c < 2; ++c) kf[t][c] = lds_frag(st + ((kgp * 2 + t) * 2 + c) * 1024 + fo);
; #pragma unroll
;     for (int et = 0; et < 4; ++et) vf[et] = lds_frag(st + 8192 + (et * 2 + kgp) * 1024 + fo);
;     const short one = (short)0x3F80;
;     const bf16x8 ones = {one, one, one, one, one, one, one, one};
; #pragma unroll
;     for (int qt = 0; qt < 2; ++qt) {
;         const int dq = d0 + qt * 16;
;         const float offq = -slope2 * (float)dq;
; #pragma unroll
;         for (int mp = 0; mp < 2; ++mp) {
;             f32x4 s[2];
; #pragma unroll
;             for (int t = 0; t < 2; ++t) s[t] = mfma16(kf[t][mp], qf[mp][qt], cb[t]);
;             if (MASKED) {
; #pragma unroll
;                 for (int j = 0; j < 8; ++j) if (dq - j < 0) s[j >> 2][j & 3] = -INFINITY;
;             }
;             const float off = offq - ub[mp][qt];
;             float pj[8];
; #pragma unroll
;             for (int j = 0; j < 8; ++j) pj[j] = ex2(fmaf(s[j >> 2][j & 3], c2, off));
;             u32x4 pu = {pk2(pj[0], pj[1]), pk2(pj[2], pj[3]), pk2(pj[4], pj[5]), pk2(pj[6], pj[7])};
;             bf16x8 pf = __builtin_bit_cast(bf16x8, pu);
; #pragma unroll
;             for (int et = 0; et < 4; ++et) o[mp][qt][et] = mfma16(vf[et], pf, o[mp][qt][et]);
;             ls[mp][qt] = mfma16(ones, pf, ls[mp][qt]);
;         }
;     }
; }
; __device__ void attn_a_item(const Params& p, int layer, int b, int h, int q128, unsigned char* smem) {
;     ...
;             if (gi == 2) {
;                 attn_tile_store(tr0, nst, tofs);
;                 attn_tile_store(tr1, nst + 32768, tofs);
;                 attn_tile_load(tr0, kbase, vbase, tl(jn - 1), tofs);
;                 attn_tile_load(tr1, kbase, vbase, tl(jn - 3), tofs);
;             }
	v_cvt_pk_bf16_f32 v230, v244, v245
	v_cvt_pk_bf16_f32 v231, v246, v247
	v_fmamk_f32 v240, v240, 0x3e8293ee, v195
	v_fmamk_f32 v241, v241, 0x3e8293ee, v195
	v_mfma_f32_16x16x32_bf16 v[40:43], v[124:127], v[228:231], v[40:43]
	v_fmamk_f32 v242, v242, 0x3e8293ee, v195
	v_fmamk_f32 v243, v243, 0x3e8293ee, v195
	v_fmamk_f32 v248, v248, 0x3e8293ee, v195
	v_fmamk_f32 v249, v249, 0x3e8293ee, v195
	v_mfma_f32_16x16x32_bf16 v[32:35], v[128:131], v[228:231], v[32:35]
	v_fmamk_f32 v250, v250, 0x3e8293ee, v195
	v_fmamk_f32 v251, v251, 0x3e8293ee, v195
	v_exp_f32_e32 v240, v240
	v_exp_f32_e32 v241, v241
	v_mfma_f32_16x16x32_bf16 v[24:27], v[132:135], v[228:231], v[24:27]
	v_exp_f32_e32 v242, v242
	v_exp_f32_e32 v243, v243
	v_exp_f32_e32 v248, v248
	v_mfma_f32_16x16x32_bf16 v[48:51], v[136:139], v[228:231], v[48:51]
	v_exp_f32_e32 v249, v249
	v_exp_f32_e32 v250, v250
	v_exp_f32_e32 v251, v251
	v_mfma_f32_16x16x32_bf16 v[92:95], v[220:223], v[228:231], v[92:95]
	v_cvt_pk_bf16_f32 v232, v240, v241
	v_cvt_pk_bf16_f32 v233, v242, v243
	v_cvt_pk_bf16_f32 v234, v248, v249
	v_cvt_pk_bf16_f32 v235, v250, v251
	s_nop 1
	v_mfma_f32_16x16x32_bf16 v[36:39], v[124:127], v[232:235], v[36:39]
	v_mfma_f32_16x16x32_bf16 v[28:31], v[128:131], v[232:235], v[28:31]
	v_mfma_f32_16x16x32_bf16 v[20:23], v[132:135], v[232:235], v[20:23]
	v_mfma_f32_16x16x32_bf16 v[44:47], v[136:139], v[232:235], v[44:47]
	v_mfma_f32_16x16x32_bf16 v[84:87], v[220:223], v[232:235], v[84:87]
	ds_read_b128 v[124:127], v190 offset:25600
	ds_read_b128 v[128:131], v190 offset:27648
	ds_read_b128 v[132:135], v190 offset:29696
	ds_read_b128 v[136:139], v190 offset:31744
	v_add_f32_e32 v204, 0x42000000, v204
	v_add_f32_e32 v205, 0x42000000, v205
	v_add_u32_e32 v252, s27, v175
	v_add_u32_e32 v253, s27, v177
	s_waitcnt vmcnt(3)
	ds_write_b128 v252, v[112:115]
	s_waitcnt vmcnt(2)
	ds_write_b128 v253, v[108:111] offset:8192
	s_waitcnt vmcnt(1)
	ds_write_b128 v252, v[116:119] offset:32768
	s_waitcnt vmcnt(0)
	ds_write_b128 v253, v[120:123] offset:40960
	global_load_dwordx4 v[112:115], v[2:3], off offset:512
	global_load_dwordx4 v[108:111], v[162:163], off
	global_load_dwordx4 v[116:119], v[164:165], off offset:512
	global_load_dwordx4 v[120:123], v[166:167], off
	v_mul_f32_e64 v192, -v176, v204
	v_sub_f32_e32 v194, v192, v179
	v_sub_f32_e32 v192, v192, v181
	s_waitcnt lgkmcnt(8)
	v_mfma_f32_16x16x32_bf16 v[196:199], v[152:155], v[4:7], v[100:103]
	v_mfma_f32_16x16x32_bf16 v[200:203], v[148:151], v[4:7], v[104:107]
	v_mfma_f32_16x16x32_bf16 v[216:219], v[144:147], v[12:15], v[100:103]
	v_mfma_f32_16x16x32_bf16 v[224:227], v[140:143], v[12:15], v[104:107]
	v_mfma_f32_16x16x32_bf16 v[152:155], v[152:155], v[8:11], v[100:103]
	v_mfma_f32_16x16x32_bf16 v[148:151], v[148:151], v[8:11], v[104:107]
	v_fma_f32 v193, -v176, v205, -v180
	v_fma_f32 v195, -v176, v205, -v182
	v_mfma_f32_16x16x32_bf16 v[144:147], v[144:147], v[16:19], v[100:103]
	v_fmamk_f32 v196, v196, 0x3e8293ee, v194
	v_fmamk_f32 v197, v197, 0x3e8293ee, v194
	v_fmamk_f32 v198, v198, 0x3e8293ee, v194
	v_fmamk_f32 v199, v199, 0x3e8293ee, v194
	v_mfma_f32_16x16x32_bf16 v[140:143], v[140:143], v[16:19], v[104:107]
	ds_read_b128 v[236:239], v190 offset:16384
	ds_read_b128 v[240:243], v190 offset:17408
	ds_read_b128 v[244:247], v190 offset:18432
	ds_read_b128 v[248:251], v190 offset:19456
	v_fmamk_f32 v200, v200, 0x3e8293ee, v194
	v_fmamk_f32 v201, v201, 0x3e8293ee, v194
	v_fmamk_f32 v202, v202, 0x3e8293ee, v194
	v_fmamk_f32 v203, v203, 0x3e8293ee, v194
	v_exp_f32_e32 v196, v196
	v_exp_f32_e32 v197, v197
	v_exp_f32_e32 v198, v198
	v_exp_f32_e32 v199, v199
	v_exp_f32_e32 v200, v200
	v_exp_f32_e32 v201, v201
	v_exp_f32_e32 v202, v202
	v_exp_f32_e32 v203, v203
	v_cvt_pk_bf16_f32 v228, v196, v197
	v_cvt_pk_bf16_f32 v229, v198, v199
	v_cvt_pk_bf16_f32 v230, v200, v201
	v_cvt_pk_bf16_f32 v231, v202, v203
	v_fmamk_f32 v216, v216, 0x3e8293ee, v192
	v_fmamk_f32 v217, v217, 0x3e8293ee, v192
	s_waitcnt lgkmcnt(8)
	v_mfma_f32_16x16x32_bf16 v[72:75], v[124:127], v[228:231], v[72:75]
	v_fmamk_f32 v218, v218, 0x3e8293ee, v192
	v_fmamk_f32 v219, v219, 0x3e8293ee, v192
	v_fmamk_f32 v224, v224, 0x3e8293ee, v192
	v_fmamk_f32 v225, v225, 0x3e8293ee, v192
	v_mfma_f32_16x16x32_bf16 v[64:67], v[128:131], v[228:231], v[64:67]
	v_fmamk_f32 v226, v226, 0x3e8293ee, v192
	v_fmamk_f32 v227, v227, 0x3e8293ee, v192
	v_exp_f32_e32 v216, v216
	v_exp_f32_e32 v217, v217
	v_mfma_f32_16x16x32_bf16 v[56:59], v[132:135], v[228:231], v[56:59]
	v_exp_f32_e32 v218, v218
	v_exp_f32_e32 v219, v219
	v_exp_f32_e32 v224, v224
	v_mfma_f32_16x16x32_bf16 v[80:83], v[136:139], v[228:231], v[80:83]
	v_exp_f32_e32 v225, v225
	v_exp_f32_e32 v226, v226
	v_exp_f32_e32 v227, v227
	v_mfma_f32_16x16x32_bf16 v[96:99], v[220:223], v[228:231], v[96:99]
	v_cvt_pk_bf16_f32 v232, v216, v217
	v_cvt_pk_bf16_f32 v233, v218, v219
	v_cvt_pk_bf16_f32 v234, v224, v225
	v_cvt_pk_bf16_f32 v235, v226, v227
	v_fmamk_f32 v152, v152, 0x3e8293ee, v193
	v_fmamk_f32 v153, v153, 0x3e8293ee, v193
	v_mfma_f32_16x16x32_bf16 v[68:71], v[124:127], v[232:235], v[68:71]
	v_fmamk_f32 v154, v154, 0x3e8293ee, v193
	v_fmamk_f32 v155, v155, 0x3e8293ee, v193
	v_fmamk_f32 v148, v148, 0x3e8293ee, v193
	v_fmamk_f32 v149, v149, 0x3e8293ee, v193
	v_mfma_f32_16x16x32_bf16 v[60:63], v[128:131], v[232:235], v[60:63]
	v_fmamk_f32 v150, v150, 0x3e8293ee, v193
	v_fmamk_f32 v151, v151, 0x3e8293ee, v193
	v_exp_f32_e32 v152, v152
	v_exp_f32_e32 v153, v153
	v_mfma_f32_16x16x32_bf16 v[52:55], v[132:135], v[232:235], v[52:55]
	v_exp_f32_e32 v154, v154
	v_exp_f32_e32 v155, v155
	v_exp_f32_e32 v148, v148
	v_mfma_f32_16x16x32_bf16 v[76:79], v[136:139], v[232:235], v[76:79]
; __device__ __forceinline__ f32x4 mfma16(bf16x8 a, bf16x8 b, f32x4 c) { return __builtin_amdgcn_mfma_f32_16x16x32_bf16(a, b, c, 0, 0, 0); }
; __device__ __forceinline__ float ex2(float x) { return __builtin_amdgcn_exp2f(x); }
; template <bool MASKED>
; __device__ __forceinline__ void diff_group(const unsigned char* st, int kgp, int fo, const bf16x8 (&qf)[2][2], f32x4 (&o)[2][2][4], f32x4 (&ls)[2][2],
;                                            const f32x4 (&cb)[2], float c2, float slope2, const float (&ub)[2][2], int d0) {
;     bf16x8 kf[2][2], vf[4];
; #pragma unroll
;     for (int t = 0; t < 2; ++t)
; #pragma unroll
;         for (int c = 0; c < 2; ++c) kf[t][c] = lds_frag(st + ((kgp * 2 + t) * 2 + c) * 1024 + fo);
; #pragma unroll
;     for (int et = 0; et < 4; ++et) vf[et] = lds_frag(st + 8192 + (et * 2 + kgp) * 1024 + fo);
;     const short one = (short)0x3F80;
;     const bf16x8 ones = {one, one, one, one, one, one, one, one};
; #pragma unroll
;     for (int qt = 0; qt < 2; ++qt) {
;         const int dq = d0 + qt * 16;
;         const float offq = -slope2 * (float)dq;
; #pragma unroll
;         for (int mp = 0; mp < 2; ++mp) {
;             f32x4 s[2];
; #pragma unroll
;             for (int t = 0; t < 2; ++t) s[t] = mfma16(kf[t][mp], qf[mp][qt], cb[t]);
;             if (MASKED) {
; #pragma unroll
;                 for (int j = 0; j < 8; ++j) if (dq - j < 0) s[j >> 2][j & 3] = -INFINITY;
;             }
;             const float off = offq - ub[mp][qt];
;             float pj[8];
; #pragma unroll
;             for (int j = 0; j < 8; ++j) pj[j] = ex2(fmaf(s[j >> 2][j & 3], c2, off));
;             u32x4 pu = {pk2(pj[0], pj[1]), pk2(pj[2], pj[3]), pk2(pj[4], pj[5]), pk2(pj[6], pj[7])};
;             bf16x8 pf = __builtin_bit_cast(bf16x8, pu);
; #pragma unroll
;             for (int et = 0; et < 4; ++et) o[mp][qt][et] = mfma16(vf[et], pf, o[mp][qt][et]);
;             ls[mp][qt] = mfma16(ones, pf, ls[mp][qt]);
;         }
;     }
; }
	v_exp_f32_e32 v149, v149
	v_exp_f32_e32 v150, v150
	v_exp_f32_e32 v151, v151
	v_mfma_f32_16x16x32_bf16 v[88:91], v[220:223], v[232:235], v[88:91]
	v_cvt_pk_bf16_f32 v228, v152, v153
	v_cvt_pk_bf16_f32 v229, v154, v155
	v_cvt_pk_bf16_f32 v230, v148, v149
	v_cvt_pk_bf16_f32 v231, v150, v151
	v_fmamk_f32 v144, v144, 0x3e8293ee, v195
	v_fmamk_f32 v145, v145, 0x3e8293ee, v195
	v_mfma_f32_16x16x32_bf16 v[40:43], v[124:127], v[228:231], v[40:43]
	v_fmamk_f32 v146, v146, 0x3e8293ee, v195
	v_fmamk_f32 v147, v147, 0x3e8293ee, v195
	v_fmamk_f32 v140, v140, 0x3e8293ee, v195
	v_fmamk_f32 v141, v141, 0x3e8293ee, v195
	v_mfma_f32_16x16x32_bf16 v[32:35], v[128:131], v[228:231], v[32:35]
	v_fmamk_f32 v142, v142, 0x3e8293ee, v195
	v_fmamk_f32 v143, v143, 0x3e8293ee, v195
	v_exp_f32_e32 v144, v144
	v_exp_f32_e32 v145, v145
	v_mfma_f32_16x16x32_bf16 v[24:27], v[132:135], v[228:231], v[24:27]
	v_exp_f32_e32 v146, v146
	v_exp_f32_e32 v147, v147
	v_exp_f32_e32 v140, v140
	v_mfma_f32_16x16x32_bf16 v[48:51], v[136:139], v[228:231], v[48:51]
	v_exp_f32_e32 v141, v141
	v_exp_f32_e32 v142, v142
	v_exp_f32_e32 v143, v143
	v_mfma_f32_16x16x32_bf16 v[92:95], v[220:223], v[228:231], v[92:95]
	v_cvt_pk_bf16_f32 v232, v144, v145
	v_cvt_pk_bf16_f32 v233, v146, v147
	v_cvt_pk_bf16_f32 v234, v140, v141
	v_cvt_pk_bf16_f32 v235, v142, v143
	s_nop 1
	v_mfma_f32_16x16x32_bf16 v[36:39], v[124:127], v[232:235], v[36:39]
	v_mfma_f32_16x16x32_bf16 v[28:31], v[128:131], v[232:235], v[28:31]
	v_mfma_f32_16x16x32_bf16 v[20:23], v[132:135], v[232:235], v[20:23]
	v_mfma_f32_16x16x32_bf16 v[44:47], v[136:139], v[232:235], v[44:47]
	v_mfma_f32_16x16x32_bf16 v[84:87], v[220:223], v[232:235], v[84:87]
	ds_read_b128 v[124:127], v190 offset:24576
	ds_read_b128 v[128:131], v190 offset:26624
	ds_read_b128 v[132:135], v190 offset:28672
	ds_read_b128 v[136:139], v190 offset:30720
	v_add_f32_e32 v204, 0x42000000, v204
	v_add_f32_e32 v205, 0x42000000, v205
	v_mul_f32_e64 v192, -v176, v204
	v_sub_f32_e32 v194, v192, v179
	v_sub_f32_e32 v192, v192, v181
	s_waitcnt lgkmcnt(4)
	v_mfma_f32_16x16x32_bf16 v[196:199], v[236:239], v[4:7], v[100:103]
	v_mfma_f32_16x16x32_bf16 v[200:203], v[244:247], v[4:7], v[104:107]
	v_mfma_f32_16x16x32_bf16 v[216:219], v[240:243], v[12:15], v[100:103]
	v_mfma_f32_16x16x32_bf16 v[224:227], v[248:251], v[12:15], v[104:107]
	v_mfma_f32_16x16x32_bf16 v[236:239], v[236:239], v[8:11], v[100:103]
	v_mfma_f32_16x16x32_bf16 v[244:247], v[244:247], v[8:11], v[104:107]
	v_fma_f32 v193, -v176, v205, -v180
	v_fma_f32 v195, -v176, v205, -v182
	v_mfma_f32_16x16x32_bf16 v[240:243], v[240:243], v[16:19], v[100:103]
	v_fmamk_f32 v196, v196, 0x3e8293ee, v194
	v_fmamk_f32 v197, v197, 0x3e8293ee, v194
	v_fmamk_f32 v198, v198, 0x3e8293ee, v194
	v_fmamk_f32 v199, v199, 0x3e8293ee, v194
	v_mfma_f32_16x16x32_bf16 v[248:251], v[248:251], v[16:19], v[104:107]
	v_fmamk_f32 v200, v200, 0x3e8293ee, v194
	v_fmamk_f32 v201, v201, 0x3e8293ee, v194
	v_fmamk_f32 v202, v202, 0x3e8293ee, v194
	v_fmamk_f32 v203, v203, 0x3e8293ee, v194
	v_exp_f32_e32 v196, v196
	v_exp_f32_e32 v197, v197
	v_exp_f32_e32 v198, v198
	v_exp_f32_e32 v199, v199
	v_exp_f32_e32 v200, v200
	v_exp_f32_e32 v201, v201
	v_exp_f32_e32 v202, v202
	v_exp_f32_e32 v203, v203
	v_cvt_pk_bf16_f32 v228, v196, v197
	v_cvt_pk_bf16_f32 v229, v198, v199
	v_cvt_pk_bf16_f32 v230, v200, v201
	v_cvt_pk_bf16_f32 v231, v202, v203
	v_fmamk_f32 v216, v216, 0x3e8293ee, v192
	v_fmamk_f32 v217, v217, 0x3e8293ee, v192
	s_waitcnt lgkmcnt(0)
	v_mfma_f32_16x16x32_bf16 v[72:75], v[124:127], v[228:231], v[72:75]
	v_fmamk_f32 v218, v218, 0x3e8293ee, v192
	v_fmamk_f32 v219, v219, 0x3e8293ee, v192
	v_fmamk_f32 v224, v224, 0x3e8293ee, v192
	v_fmamk_f32 v225, v225, 0x3e8293ee, v192
	v_mfma_f32_16x16x32_bf16 v[64:67], v[128:131], v[228:231], v[64:67]
	v_fmamk_f32 v226, v226, 0x3e8293ee, v192
	v_fmamk_f32 v227, v227, 0x3e8293ee, v192
	v_exp_f32_e32 v216, v216
	v_exp_f32_e32 v217, v217
	v_mfma_f32_16x16x32_bf16 v[56:59], v[132:135], v[228:231], v[56:59]
	v_exp_f32_e32 v218, v218
	v_exp_f32_e32 v219, v219
	v_exp_f32_e32 v224, v224
	v_mfma_f32_16x16x32_bf16 v[80:83], v[136:139], v[228:231], v[80:83]
	v_exp_f32_e32 v225, v225
	v_exp_f32_e32 v226, v226
	v_exp_f32_e32 v227, v227
	v_mfma_f32_16x16x32_bf16 v[96:99], v[220:223], v[228:231], v[96:99]
	v_cvt_pk_bf16_f32 v232, v216, v217
	v_cvt_pk_bf16_f32 v233, v218, v219
	v_cvt_pk_bf16_f32 v234, v224, v225
	v_cvt_pk_bf16_f32 v235, v226, v227
	v_fmamk_f32 v236, v236, 0x3e8293ee, v193
	v_fmamk_f32 v237, v237, 0x3e8293ee, v193
	v_mfma_f32_16x16x32_bf16 v[68:71], v[124:127], v[232:235], v[68:71]
	v_fmamk_f32 v238, v238, 0x3e8293ee, v193
	v_fmamk_f32 v239, v239, 0x3e8293ee, v193
	v_fmamk_f32 v244, v244, 0x3e8293ee, v193
	v_fmamk_f32 v245, v245, 0x3e8293ee, v193
	v_mfma_f32_16x16x32_bf16 v[60:63], v[128:131], v[232:235], v[60:63]
	v_fmamk_f32 v246, v246, 0x3e8293ee, v193
	v_fmamk_f32 v247, v247, 0x3e8293ee, v193
	v_exp_f32_e32 v236, v236
	v_exp_f32_e32 v237, v237
	v_mfma_f32_16x16x32_bf16 v[52:55], v[132:135], v[232:235], v[52:55]
	v_exp_f32_e32 v238, v238
	v_exp_f32_e32 v239, v239
	v_exp_f32_e32 v244, v244
	v_mfma_f32_16x16x32_bf16 v[76:79], v[136:139], v[232:235], v[76:79]
	v_exp_f32_e32 v245, v245
	v_exp_f32_e32 v246, v246
	v_exp_f32_e32 v247, v247
	v_mfma_f32_16x16x32_bf16 v[88:91], v[220:223], v[232:235], v[88:91]
	v_cvt_pk_bf16_f32 v228, v236, v237
	v_cvt_pk_bf16_f32 v229, v238, v239
	v_cvt_pk_bf16_f32 v230, v244, v245
	v_cvt_pk_bf16_f32 v231, v246, v247
	v_fmamk_f32 v240, v240, 0x3e8293ee, v195
	v_fmamk_f32 v241, v241, 0x3e8293ee, v195
	v_mfma_f32_16x16x32_bf16 v[40:43], v[124:127], v[228:231], v[40:43]
	v_fmamk_f32 v242, v242, 0x3e8293ee, v195
	v_fmamk_f32 v243, v243, 0x3e8293ee, v195
	v_fmamk_f32 v248, v248, 0x3e8293ee, v195
	v_fmamk_f32 v249, v249, 0x3e8293ee, v195
	v_mfma_f32_16x16x32_bf16 v[32:35], v[128:131], v[228:231], v[32:35]
	v_fmamk_f32 v250, v250, 0x3e8293ee, v195
	v_fmamk_f32 v251, v251, 0x3e8293ee, v195
	v_exp_f32_e32 v240, v240
	v_exp_f32_e32 v241, v241
	v_mfma_f32_16x16x32_bf16 v[24:27], v[132:135], v[228:231], v[24:27]
	v_exp_f32_e32 v242, v242
	v_exp_f32_e32 v243, v243
	v_exp_f32_e32 v248, v248
	v_mfma_f32_16x16x32_bf16 v[48:51], v[136:139], v[228:231], v[48:51]
	v_exp_f32_e32 v249, v249
	v_exp_f32_e32 v250, v250
	v_exp_f32_e32 v251, v251
	v_mfma_f32_16x16x32_bf16 v[92:95], v[220:223], v[228:231], v[92:95]
	v_cvt_pk_bf16_f32 v232, v240, v241
	v_cvt_pk_bf16_f32 v233, v242, v243
	v_cvt_pk_bf16_f32 v234, v248, v249
	v_cvt_pk_bf16_f32 v235, v250, v251
	s_nop 1
	v_mfma_f32_16x16x32_bf16 v[36:39], v[124:127], v[232:235], v[36:39]
	v_mfma_f32_16x16x32_bf16 v[28:31], v[128:131], v[232:235], v[28:31]
	v_mfma_f32_16x16x32_bf16 v[20:23], v[132:135], v[232:235], v[20:23]
	v_mfma_f32_16x16x32_bf16 v[44:47], v[136:139], v[232:235], v[44:47]
	v_mfma_f32_16x16x32_bf16 v[84:87], v[220:223], v[232:235], v[84:87]
	s_branch .LBB0_436

; template <bool MASKED>
; __device__ __forceinline__ void diff_group(const unsigned char* st, int kgp, int fo, const bf16x8 (&qf)[2][2], f32x4 (&o)[2][2][4], f32x4 (&ls)[2][2],
;                                            const f32x4 (&cb)[2], float c2, float slope2, const float (&ub)[2][2], int d0) {
;     bf16x8 kf[2][2], vf[4];
; #pragma unroll
;     for (int t = 0; t < 2; ++t)
; #pragma unroll
;         for (int c = 0; c < 2; ++c) kf[t][c] = lds_frag(st + ((kgp * 2 + t) * 2 + c) * 1024 + fo);
; #pragma unroll
;     for (int et = 0; et < 4; ++et) vf[et] = lds_frag(st + 8192 + (et * 2 + kgp) * 1024 + fo);
;     const short one = (short)0x3F80;
;     const bf16x8 ones = {one, one, one, one, one, one, one, one};
; #pragma unroll
;     for (int qt = 0; qt < 2; ++qt) {
;         const int dq = d0 + qt * 16;
;         const float offq = -slope2 * (float)dq;
; #pragma unroll
;         for (int mp = 0; mp < 2; ++mp) {
;             f32x4 s[2];
; #pragma unroll
;             for (int t = 0; t < 2; ++t) s[t] = mfma16(kf[t][mp], qf[mp][qt], cb[t]);
;             if (MASKED) {
; #pragma unroll
;                 for (int j = 0; j < 8; ++j) if (dq - j < 0) s[j >> 2][j & 3] = -INFINITY;
;             }
;             const float off = offq - ub[mp][qt];
;             float pj[8];
; #pragma unroll
;             for (int j = 0; j < 8; ++j) pj[j] = ex2(fmaf(s[j >> 2][j & 3], c2, off));
;             u32x4 pu = {pk2(pj[0], pj[1]), pk2(pj[2], pj[3]), pk2(pj[4], pj[5]), pk2(pj[6], pj[7])};
;             bf16x8 pf = __builtin_bit_cast(bf16x8, pu);
; #pragma unroll
;             for (int et = 0; et < 4; ++et) o[mp][qt][et] = mfma16(vf[et], pf, o[mp][qt][et]);
;             ls[mp][qt] = mfma16(ones, pf, ls[mp][qt]);
;         }
;     }
; }
; __device__ void attn_a_item(const Params& p, int layer, int b, int h, int q128, unsigned char* smem) {
;     ...
;             const int jt = jw - (gi >> 1), kk = 1 - (gi & 1);
;             const int g = jt * 2 + kk;
;             if (g >= 0 && g <= gmax && !done) {
;                 const int dmin = qw0 - (g * 32 + 31);
;                 if (slope2 * (float)dmin > thr) done = true;
;                 else {
;                     const unsigned char* st = st0 + (gi >> 1) * 16384;
;                     const int d0 = (qw0 + l15) - (g * 32 + kg * 8);
;                     if (g == gmax) diff_group<true>(st, kk, fo, qf, o, ls, cb, c2, slope2, ub, d0);
.LBB0_443:
	s_lshr_b32 s4, s28, 1
	s_waitcnt lgkmcnt(3)
	v_add_u32_e32 v124, s4, v0
	v_sub_u32_e32 v125, s82, v124
	v_lshlrev_b32_e32 v124, 1, v125
	v_bitop3_b32 v124, v124, s28, 1 bitop3:0xf2
	v_cmp_gt_i32_e32 vcc, 0, v125
	v_cmp_gt_i32_e64 s[2:3], v124, v183
	s_or_b64 s[2:3], vcc, s[2:3]
	s_nor_b64 s[2:3], s[2:3], s[16:17]
	s_and_saveexec_b64 s[18:19], s[2:3]
	s_cbranch_execz .LBB0_440
	v_lshlrev_b32_e32 v125, 5, v124
	v_sub_u32_e32 v126, v184, v125
	v_cvt_f32_i32_e32 v126, v126
	s_mov_b32 s2, 0x43168000
	v_mul_f32_e32 v126, v176, v126
	v_cmp_nlt_f32_e32 vcc, s2, v126
	s_mov_b64 s[2:3], -1
	s_and_saveexec_b64 s[20:21], vcc
	s_cbranch_execz .LBB0_439
	s_andn2_b32 s2, 1, s28
	v_sub_u32_e32 v125, 0, v125
	v_cmp_ne_u32_e32 vcc, v124, v183
	v_lshl_add_u32 v124, s4, 14, v190
	v_add_u32_e32 v193, v125, v185
	v_lshl_add_u32 v125, s2, 12, v124
	ds_read_b128 v[152:155], v125
	ds_read_b128 v[144:147], v125 offset:1024
	ds_read_b128 v[148:151], v125 offset:2048
	ds_read_b128 v[140:143], v125 offset:3072
	s_waitcnt lgkmcnt(4)
	v_lshl_add_u32 v136, s2, 10, v124
	v_cvt_f32_i32_e32 v192, v193
	ds_read_b128 v[124:127], v136 offset:8192
	ds_read_b128 v[128:131], v136 offset:10240
	ds_read_b128 v[132:135], v136 offset:12288
	ds_read_b128 v[136:139], v136 offset:14336
	v_add_u32_e32 v191, 16, v193
	v_cvt_f32_i32_e32 v191, v191
	v_mul_f32_e64 v192, -v176, v192
	v_sub_f32_e32 v194, v192, v179
	v_sub_f32_e32 v192, v192, v181
	s_and_saveexec_b64 s[2:3], vcc
	s_xor_b64 s[2:3], exec, s[2:3]
	s_cbranch_execz .LBB0_447
	s_waitcnt lgkmcnt(4)
	v_mfma_f32_16x16x32_bf16 v[196:199], v[152:155], v[4:7], v[100:103]
	s_mov_b32 s46, s44
	v_mfma_f32_16x16x32_bf16 v[200:203], v[148:151], v[4:7], v[104:107]
	s_mov_b32 s47, s44
	v_mfma_f32_16x16x32_bf16 v[216:219], v[144:147], v[12:15], v[100:103]
	s_mov_b32 s45, s44
	v_mfma_f32_16x16x32_bf16 v[224:227], v[140:143], v[12:15], v[104:107]
	v_mfma_f32_16x16x32_bf16 v[152:155], v[152:155], v[8:11], v[100:103]
	v_mfma_f32_16x16x32_bf16 v[148:151], v[148:151], v[8:11], v[104:107]
	v_fma_f32 v193, -v176, v191, -v180
	v_fma_f32 v195, -v176, v191, -v182
	v_mfma_f32_16x16x32_bf16 v[144:147], v[144:147], v[16:19], v[100:103]
	v_fmamk_f32 v196, v196, 0x3e8293ee, v194
	v_fmamk_f32 v197, v197, 0x3e8293ee, v194
	v_fmamk_f32 v198, v198, 0x3e8293ee, v194
	v_fmamk_f32 v199, v199, 0x3e8293ee, v194
	v_mfma_f32_16x16x32_bf16 v[140:143], v[140:143], v[16:19], v[104:107]
	v_fmamk_f32 v200, v200, 0x3e8293ee, v194
	v_fmamk_f32 v201, v201, 0x3e8293ee, v194
	v_fmamk_f32 v202, v202, 0x3e8293ee, v194
	v_fmamk_f32 v203, v203, 0x3e8293ee, v194
	v_exp_f32_e32 v196, v196
	v_exp_f32_e32 v197, v197
	v_exp_f32_e32 v198, v198
	v_exp_f32_e32 v199, v199
	v_exp_f32_e32 v200, v200
	v_exp_f32_e32 v201, v201
	v_exp_f32_e32 v202, v202
	v_exp_f32_e32 v203, v203
	v_cvt_pk_bf16_f32 v228, v196, v197
	v_cvt_pk_bf16_f32 v229, v198, v199
	v_cvt_pk_bf16_f32 v230, v200, v201
	v_cvt_pk_bf16_f32 v231, v202, v203
	v_fmamk_f32 v216, v216, 0x3e8293ee, v192
	v_fmamk_f32 v217, v217, 0x3e8293ee, v192
	s_waitcnt lgkmcnt(0)
	v_mfma_f32_16x16x32_bf16 v[72:75], v[124:127], v[228:231], v[72:75]
	v_fmamk_f32 v218, v218, 0x3e8293ee, v192
	v_fmamk_f32 v219, v219, 0x3e8293ee, v192
	v_fmamk_f32 v224, v224, 0x3e8293ee, v192
	v_fmamk_f32 v225, v225, 0x3e8293ee, v192
	v_mfma_f32_16x16x32_bf16 v[64:67], v[128:131], v[228:231], v[64:67]
	v_fmamk_f32 v226, v226, 0x3e8293ee, v192
	v_fmamk_f32 v227, v227, 0x3e8293ee, v192
	v_exp_f32_e32 v216, v216
	v_exp_f32_e32 v217, v217
	v_mfma_f32_16x16x32_bf16 v[56:59], v[132:135], v[228:231], v[56:59]
	v_exp_f32_e32 v218, v218
	v_exp_f32_e32 v219, v219
	v_exp_f32_e32 v224, v224
	v_mfma_f32_16x16x32_bf16 v[80:83], v[136:139], v[228:231], v[80:83]
	v_exp_f32_e32 v225, v225
	v_exp_f32_e32 v226, v226
	v_exp_f32_e32 v227, v227
	v_mfma_f32_16x16x32_bf16 v[96:99], v[220:223], v[228:231], v[96:99]
	v_cvt_pk_bf16_f32 v232, v216, v217
	v_cvt_pk_bf16_f32 v233, v218, v219
	v_cvt_pk_bf16_f32 v234, v224, v225
	v_cvt_pk_bf16_f32 v235, v226, v227
	v_fmamk_f32 v152, v152, 0x3e8293ee, v193
	v_fmamk_f32 v153, v153, 0x3e8293ee, v193
	v_mfma_f32_16x16x32_bf16 v[68:71], v[124:127], v[232:235], v[68:71]
	v_fmamk_f32 v154, v154, 0x3e8293ee, v193
	v_fmamk_f32 v155, v155, 0x3e8293ee, v193
	v_fmamk_f32 v148, v148, 0x3e8293ee, v193
	v_fmamk_f32 v149, v149, 0x3e8293ee, v193
	v_mfma_f32_16x16x32_bf16 v[60:63], v[128:131], v[232:235], v[60:63]
	v_fmamk_f32 v150, v150, 0x3e8293ee, v193
	v_fmamk_f32 v151, v151, 0x3e8293ee, v193
	v_exp_f32_e32 v152, v152
	v_exp_f32_e32 v153, v153
	v_mfma_f32_16x16x32_bf16 v[52:55], v[132:135], v[232:235], v[52:55]
	v_exp_f32_e32 v154, v154
	v_exp_f32_e32 v155, v155
	v_exp_f32_e32 v148, v148
	v_mfma_f32_16x16x32_bf16 v[76:79], v[136:139], v[232:235], v[76:79]
	v_exp_f32_e32 v149, v149
	v_exp_f32_e32 v150, v150
	v_exp_f32_e32 v151, v151
	v_mfma_f32_16x16x32_bf16 v[88:91], v[220:223], v[232:235], v[88:91]
	v_cvt_pk_bf16_f32 v228, v152, v153
	v_cvt_pk_bf16_f32 v229, v154, v155
	v_cvt_pk_bf16_f32 v230, v148, v149
	v_cvt_pk_bf16_f32 v231, v150, v151
	v_fmamk_f32 v144, v144, 0x3e8293ee, v195
	v_fmamk_f32 v145, v145, 0x3e8293ee, v195
	v_mfma_f32_16x16x32_bf16 v[40:43], v[124:127], v[228:231], v[40:43]
	v_fmamk_f32 v146, v146, 0x3e8293ee, v195
	v_fmamk_f32 v147, v147, 0x3e8293ee, v195
	v_fmamk_f32 v140, v140, 0x3e8293ee, v195
	v_fmamk_f32 v141, v141, 0x3e8293ee, v195
	v_mfma_f32_16x16x32_bf16 v[32:35], v[128:131], v[228:231], v[32:35]
	v_fmamk_f32 v142, v142, 0x3e8293ee, v195
	v_fmamk_f32 v143, v143, 0x3e8293ee, v195
	v_exp_f32_e32 v144, v144
	v_exp_f32_e32 v145, v145
	v_mfma_f32_16x16x32_bf16 v[24:27], v[132:135], v[228:231], v[24:27]
	v_exp_f32_e32 v146, v146
	v_exp_f32_e32 v147, v147
	v_exp_f32_e32 v140, v140
	v_mfma_f32_16x16x32_bf16 v[48:51], v[136:139], v[228:231], v[48:51]
	v_exp_f32_e32 v141, v141
	v_exp_f32_e32 v142, v142
	v_exp_f32_e32 v143, v143
	v_mfma_f32_16x16x32_bf16 v[92:95], v[220:223], v[228:231], v[92:95]
	v_cvt_pk_bf16_f32 v232, v144, v145
	v_cvt_pk_bf16_f32 v233, v146, v147
	v_cvt_pk_bf16_f32 v234, v140, v141
	v_cvt_pk_bf16_f32 v235, v142, v143
	s_nop 1
	v_mfma_f32_16x16x32_bf16 v[36:39], v[124:127], v[232:235], v[36:39]
	v_mfma_f32_16x16x32_bf16 v[28:31], v[128:131], v[232:235], v[28:31]
	v_mfma_f32_16x16x32_bf16 v[20:23], v[132:135], v[232:235], v[20:23]
	v_mfma_f32_16x16x32_bf16 v[44:47], v[136:139], v[232:235], v[44:47]
	v_mfma_f32_16x16x32_bf16 v[84:87], v[220:223], v[232:235], v[84:87]
